# attention D const loops: K/V LDS staging stores moved from pre-barrier tail into the P.V MFMA shadow
# speedup vs baseline: 1.0105x; 1.0050x over previous
.LBB0_465:
	s_add_i32 s57, s58, 1
	s_and_b32 s29, s55, 0x1fc000
	s_add_u32 s60, s48, s29
	s_addc_u32 s61, s49, 0
	s_and_b32 s29, s53, 0x1fc0
	s_mul_i32 s29, s29, 0x8c00
	global_load_dwordx4 v[162:165], v201, s[60:61]
	global_load_dwordx4 v[166:169], v208, s[60:61]
	s_add_u32 s60, s50, s29
	s_addc_u32 s61, s51, 0
	global_load_dwordx4 v[170:173], v209, s[60:61]
	global_load_dwordx4 v[174:177], v210, s[60:61]
	s_and_b32 s58, s58, 1
	s_mul_i32 s29, s58, 0x4400
	v_add_u32_e32 v186, s29, v195
	ds_read_b128 v[96:99], v186
	ds_read_b128 v[224:227], v186 offset:32
	ds_read_b128 v[228:231], v186 offset:8704
	ds_read_b128 v[232:235], v186 offset:8736
	s_xor_b32 s29, s58, 1
	s_mulk_i32 s29, 0x5000
	v_add_u32_e32 v187, s29, v202
	ds_read_b128 v[236:239], v186 offset:64
	ds_read_b64_tr_b16 v[240:241], v187 offset:34816
	ds_read_b64_tr_b16 v[242:243], v187 offset:37376
	v_dot2c_f32_bf16_e32 v222, 0x3f803f80, v158
	v_dot2c_f32_bf16_e32 v223, 0x3f803f80, v159
	s_waitcnt lgkmcnt(6)
	v_mfma_f32_32x32x16_bf16 v[112:127], v[96:99], v[130:133], v[80:95]
	s_waitcnt lgkmcnt(4)
	v_mfma_f32_32x32x16_bf16 v[96:111], v[228:231], v[130:133], v[80:95]
	ds_read_b128 v[228:231], v186 offset:8768
	ds_read_b64_tr_b16 v[244:245], v187 offset:34880
	ds_read_b64_tr_b16 v[246:247], v187 offset:37440
	v_dot2c_f32_bf16_e32 v221, 0x3f803f80, v160
	v_dot2c_f32_bf16_e32 v211, 0x3f803f80, v161
	v_mfma_f32_32x32x16_bf16 v[112:127], v[224:227], v[134:137], v[112:127]
	ds_read_b128 v[224:227], v186 offset:96
	ds_read_b64_tr_b16 v[248:249], v187 offset:34944
	ds_read_b64_tr_b16 v[250:251], v187 offset:37504
	v_dot2c_f32_bf16_e32 v222, 0x3f803f80, v154
	v_dot2c_f32_bf16_e32 v223, 0x3f803f80, v155
	s_waitcnt lgkmcnt(9)
	v_mfma_f32_32x32x16_bf16 v[96:111], v[232:235], v[134:137], v[96:111]
	ds_read_b128 v[232:235], v186 offset:8800
	ds_read_b64_tr_b16 v[214:215], v187 offset:35008
	ds_read_b64_tr_b16 v[216:217], v187 offset:37568
	v_dot2c_f32_bf16_e32 v221, 0x3f803f80, v156
	v_dot2c_f32_bf16_e32 v211, 0x3f803f80, v157
	v_dot2c_f32_bf16_e32 v222, 0x3f803f80, v150
	v_dot2c_f32_bf16_e32 v223, 0x3f803f80, v151
	s_waitcnt lgkmcnt(11)
	v_mfma_f32_32x32x16_bf16 v[112:127], v[236:239], v[138:141], v[112:127]
	v_dot2c_f32_bf16_e32 v221, 0x3f803f80, v152
	v_dot2c_f32_bf16_e32 v211, 0x3f803f80, v153
	s_waitcnt lgkmcnt(8)
	v_mfma_f32_32x32x16_bf16 v[96:111], v[228:231], v[138:141], v[96:111]
	v_dot2c_f32_bf16_e32 v222, 0x3f803f80, v146
	v_dot2c_f32_bf16_e32 v223, 0x3f803f80, v147
	s_waitcnt lgkmcnt(5)
	v_mfma_f32_32x32x16_bf16 v[112:127], v[224:227], v[142:145], v[112:127]
	v_dot2c_f32_bf16_e32 v221, 0x3f803f80, v148
	v_dot2c_f32_bf16_e32 v211, 0x3f803f80, v149
	s_waitcnt lgkmcnt(2)
	v_mfma_f32_32x32x16_bf16 v[96:111], v[232:235], v[142:145], v[96:111]
	v_mfma_f32_32x32x16_bf16 v[64:79], v[240:243], v[158:161], v[64:79]
	ds_read_b64_tr_b16 v[224:225], v187 offset:39936
	ds_read_b64_tr_b16 v[226:227], v187 offset:42496
	s_nop 4
	v_exp_f32_e32 v186, v112
	v_exp_f32_e32 v188, v113
	v_mfma_f32_32x32x16_bf16 v[48:63], v[244:247], v[158:161], v[48:63]
	ds_read_b64_tr_b16 v[228:229], v187 offset:40000
	ds_read_b64_tr_b16 v[230:231], v187 offset:42560
	v_exp_f32_e32 v189, v114
	v_exp_f32_e32 v212, v115
	v_mfma_f32_32x32x16_bf16 v[32:47], v[248:251], v[158:161], v[32:47]
	ds_read_b64_tr_b16 v[112:113], v187 offset:40064
	ds_read_b64_tr_b16 v[114:115], v187 offset:42624
	v_exp_f32_e32 v213, v116
	v_exp_f32_e32 v232, v117
	s_waitcnt lgkmcnt(6)
	v_mfma_f32_32x32x16_bf16 v[16:31], v[214:217], v[158:161], v[16:31]
	ds_read_b64_tr_b16 v[158:159], v187 offset:40128
	ds_read_b64_tr_b16 v[160:161], v187 offset:42688
	v_exp_f32_e32 v233, v118
	v_exp_f32_e32 v234, v119
	s_waitcnt lgkmcnt(6)
	v_mfma_f32_32x32x16_bf16 v[64:79], v[224:227], v[154:157], v[64:79]
	ds_read_b64_tr_b16 v[116:117], v187 offset:45056
	ds_read_b64_tr_b16 v[118:119], v187 offset:47616
	v_exp_f32_e32 v224, v120
	v_exp_f32_e32 v225, v121
	s_waitcnt lgkmcnt(6)
	v_mfma_f32_32x32x16_bf16 v[48:63], v[228:231], v[154:157], v[48:63]
	ds_read_b64_tr_b16 v[214:215], v187 offset:45120
	ds_read_b64_tr_b16 v[216:217], v187 offset:47680
	v_exp_f32_e32 v226, v122
	v_exp_f32_e32 v227, v123
	s_waitcnt lgkmcnt(6)
	v_mfma_f32_32x32x16_bf16 v[32:47], v[112:115], v[154:157], v[32:47]
	ds_read_b64_tr_b16 v[112:113], v187 offset:45184
	ds_read_b64_tr_b16 v[114:115], v187 offset:47744
	v_exp_f32_e32 v228, v124
	v_exp_f32_e32 v229, v125
	s_waitcnt lgkmcnt(6)
	v_mfma_f32_32x32x16_bf16 v[16:31], v[158:161], v[154:157], v[16:31]
	ds_read_b64_tr_b16 v[120:121], v187 offset:45248
	ds_read_b64_tr_b16 v[122:123], v187 offset:47808
	v_exp_f32_e32 v154, v126
	v_exp_f32_e32 v155, v127
	s_waitcnt lgkmcnt(6)
	v_mfma_f32_32x32x16_bf16 v[64:79], v[116:119], v[150:153], v[64:79]
	ds_read_b64_tr_b16 v[116:117], v187 offset:50176
	ds_read_b64_tr_b16 v[118:119], v187 offset:52736
	v_exp_f32_e32 v156, v96
	v_exp_f32_e32 v157, v97
	s_waitcnt lgkmcnt(6)
	v_mfma_f32_32x32x16_bf16 v[48:63], v[214:217], v[150:153], v[48:63]
	ds_read_b64_tr_b16 v[124:125], v187 offset:50240
	ds_read_b64_tr_b16 v[126:127], v187 offset:52800
	v_exp_f32_e32 v158, v98
	v_exp_f32_e32 v159, v99
	s_waitcnt lgkmcnt(6)
	v_mfma_f32_32x32x16_bf16 v[32:47], v[112:115], v[150:153], v[32:47]
	ds_read_b64_tr_b16 v[96:97], v187 offset:50304
	ds_read_b64_tr_b16 v[98:99], v187 offset:52864
	v_exp_f32_e32 v100, v100
	v_exp_f32_e32 v101, v101
	s_waitcnt lgkmcnt(6)
	v_mfma_f32_32x32x16_bf16 v[16:31], v[120:123], v[150:153], v[16:31]
	ds_read_b64_tr_b16 v[112:113], v187 offset:50368
	ds_read_b64_tr_b16 v[114:115], v187 offset:52928
	s_bitcmp1_b32 s57, 0
	s_cselect_b32 s29, 0x4400, 0
	s_add_i32 s29, s29, 0
	v_add_u32_e32 v187, s29, v182
	s_mulk_i32 s58, 0x5000
	s_waitcnt vmcnt(3)
	ds_write_b128 v187, v[162:165]
	v_add_u32_e32 v187, s29, v190
	s_add_i32 s29, s58, 0
	s_waitcnt vmcnt(2)
	ds_write_b128 v187, v[166:169]
	v_add_u32_e32 v187, s29, v196
	s_waitcnt vmcnt(1)
	ds_write_b128 v187, v[170:173] offset:34816
	v_add_u32_e32 v187, s29, v198
	s_waitcnt vmcnt(0)
	ds_write_b128 v187, v[174:177] offset:34816
	v_exp_f32_e32 v102, v102
	v_exp_f32_e32 v103, v103
	s_waitcnt lgkmcnt(10)
	v_mfma_f32_32x32x16_bf16 v[64:79], v[116:119], v[146:149], v[64:79]
	v_exp_f32_e32 v104, v104
	v_exp_f32_e32 v105, v105
	s_waitcnt lgkmcnt(8)
	v_mfma_f32_32x32x16_bf16 v[48:63], v[124:127], v[146:149], v[48:63]
	v_exp_f32_e32 v106, v106
	v_exp_f32_e32 v107, v107
	s_waitcnt lgkmcnt(6)
	v_mfma_f32_32x32x16_bf16 v[32:47], v[96:99], v[146:149], v[32:47]
	v_exp_f32_e32 v96, v108
	v_exp_f32_e32 v97, v109
	s_waitcnt lgkmcnt(4)
	v_mfma_f32_32x32x16_bf16 v[16:31], v[112:115], v[146:149], v[16:31]
	v_cvt_pk_bf16_f32 v148, v96, v97
	v_cvt_pk_bf16_f32 v147, v106, v107
	v_cvt_pk_bf16_f32 v146, v104, v105
	v_cvt_pk_bf16_f32 v153, v102, v103
	v_cvt_pk_bf16_f32 v152, v100, v101
	v_cvt_pk_bf16_f32 v151, v158, v159
	v_cvt_pk_bf16_f32 v150, v156, v157
	v_cvt_pk_bf16_f32 v157, v154, v155
	v_cvt_pk_bf16_f32 v156, v228, v229
	v_cvt_pk_bf16_f32 v155, v226, v227
	v_cvt_pk_bf16_f32 v154, v224, v225
	v_cvt_pk_bf16_f32 v161, v233, v234
	v_cvt_pk_bf16_f32 v160, v213, v232
	v_cvt_pk_bf16_f32 v159, v189, v212
	v_cvt_pk_bf16_f32 v158, v186, v188
	v_exp_f32_e32 v98, v110
	v_exp_f32_e32 v99, v111
	s_add_i32 s53, s53, 64
	s_addk_i32 s55, 0x4000
	v_cvt_pk_bf16_f32 v149, v98, v99
	s_cmp_eq_u32 s52, s57
	s_mov_b32 s58, s57
	s_waitcnt lgkmcnt(0)
	s_barrier
	s_cbranch_scc0 .LBB0_465
	s_mov_b32 s57, s54
	s_branch .LBB0_468

.LBB0_479:
	s_add_i32 s55, s54, 1
	s_and_b32 s29, s53, 0x1fc000
	s_cmpk_lg_i32 s54, 0x7f
	s_cselect_b32 s29, s29, 0x1fc000
	s_add_u32 s56, s48, s29
	s_addc_u32 s57, s49, 0
	global_load_dwordx4 v[170:173], v201, s[56:57]
	global_load_dwordx4 v[174:177], v208, s[56:57]
	s_add_u32 s56, s50, s52
	s_addc_u32 s57, s51, 0
	global_load_dwordx4 v[162:165], v209, s[56:57]
	global_load_dwordx4 v[166:169], v210, s[56:57]
	s_and_b32 s56, s54, 1
	s_mul_i32 s29, s56, 0x4400
	v_add_u32_e32 v186, s29, v195
	ds_read_b128 v[96:99], v186
	ds_read_b128 v[214:217], v186 offset:32
	ds_read_b128 v[224:227], v186 offset:8704
	ds_read_b128 v[228:231], v186 offset:8736
	s_xor_b32 s29, s56, 1
	s_mulk_i32 s29, 0x5000
	v_add_u32_e32 v187, s29, v202
	ds_read_b128 v[232:235], v186 offset:64
	ds_read_b64_tr_b16 v[236:237], v187 offset:34816
	ds_read_b64_tr_b16 v[238:239], v187 offset:37376
	v_dot2c_f32_bf16_e32 v222, 0x3f803f80, v158
	v_dot2c_f32_bf16_e32 v223, 0x3f803f80, v159
	s_waitcnt lgkmcnt(6)
	v_mfma_f32_32x32x16_bf16 v[112:127], v[96:99], v[130:133], v[80:95]
	s_waitcnt lgkmcnt(4)
	v_mfma_f32_32x32x16_bf16 v[96:111], v[224:227], v[130:133], v[80:95]
	ds_read_b128 v[224:227], v186 offset:8768
	ds_read_b64_tr_b16 v[240:241], v187 offset:34880
	ds_read_b64_tr_b16 v[242:243], v187 offset:37440
	v_dot2c_f32_bf16_e32 v221, 0x3f803f80, v160
	v_dot2c_f32_bf16_e32 v211, 0x3f803f80, v161
	v_mfma_f32_32x32x16_bf16 v[112:127], v[214:217], v[134:137], v[112:127]
	ds_read_b128 v[214:217], v186 offset:96
	ds_read_b64_tr_b16 v[244:245], v187 offset:34944
	ds_read_b64_tr_b16 v[246:247], v187 offset:37504
	v_dot2c_f32_bf16_e32 v222, 0x3f803f80, v154
	v_dot2c_f32_bf16_e32 v223, 0x3f803f80, v155
	s_waitcnt lgkmcnt(9)
	v_mfma_f32_32x32x16_bf16 v[96:111], v[228:231], v[134:137], v[96:111]
	ds_read_b128 v[228:231], v186 offset:8800
	ds_read_b64_tr_b16 v[248:249], v187 offset:35008
	ds_read_b64_tr_b16 v[250:251], v187 offset:37568
	v_dot2c_f32_bf16_e32 v221, 0x3f803f80, v156
	v_dot2c_f32_bf16_e32 v211, 0x3f803f80, v157
	v_dot2c_f32_bf16_e32 v222, 0x3f803f80, v150
	v_dot2c_f32_bf16_e32 v223, 0x3f803f80, v151
	s_waitcnt lgkmcnt(11)
	v_mfma_f32_32x32x16_bf16 v[112:127], v[232:235], v[138:141], v[112:127]
	v_dot2c_f32_bf16_e32 v221, 0x3f803f80, v152
	v_dot2c_f32_bf16_e32 v211, 0x3f803f80, v153
	s_waitcnt lgkmcnt(8)
	v_mfma_f32_32x32x16_bf16 v[96:111], v[224:227], v[138:141], v[96:111]
	v_dot2c_f32_bf16_e32 v222, 0x3f803f80, v146
	v_dot2c_f32_bf16_e32 v223, 0x3f803f80, v147
	s_waitcnt lgkmcnt(5)
	v_mfma_f32_32x32x16_bf16 v[112:127], v[214:217], v[142:145], v[112:127]
	v_dot2c_f32_bf16_e32 v221, 0x3f803f80, v148
	v_dot2c_f32_bf16_e32 v211, 0x3f803f80, v149
	s_waitcnt lgkmcnt(2)
	v_mfma_f32_32x32x16_bf16 v[96:111], v[228:231], v[142:145], v[96:111]
	v_mfma_f32_32x32x16_bf16 v[64:79], v[236:239], v[158:161], v[64:79]
	ds_read_b64_tr_b16 v[214:215], v187 offset:39936
	ds_read_b64_tr_b16 v[216:217], v187 offset:42496
	s_nop 4
	v_exp_f32_e32 v186, v112
	v_exp_f32_e32 v188, v113
	v_mfma_f32_32x32x16_bf16 v[48:63], v[240:243], v[158:161], v[48:63]
	ds_read_b64_tr_b16 v[224:225], v187 offset:40000
	ds_read_b64_tr_b16 v[226:227], v187 offset:42560
	v_exp_f32_e32 v189, v114
	v_exp_f32_e32 v212, v115
	v_mfma_f32_32x32x16_bf16 v[32:47], v[244:247], v[158:161], v[32:47]
	ds_read_b64_tr_b16 v[112:113], v187 offset:40064
	ds_read_b64_tr_b16 v[114:115], v187 offset:42624
	v_exp_f32_e32 v213, v116
	v_exp_f32_e32 v228, v117
	s_waitcnt lgkmcnt(6)
	v_mfma_f32_32x32x16_bf16 v[16:31], v[248:251], v[158:161], v[16:31]
	ds_read_b64_tr_b16 v[158:159], v187 offset:40128
	ds_read_b64_tr_b16 v[160:161], v187 offset:42688
	v_exp_f32_e32 v229, v118
	v_exp_f32_e32 v230, v119
	s_waitcnt lgkmcnt(6)
	v_mfma_f32_32x32x16_bf16 v[64:79], v[214:217], v[154:157], v[64:79]
	ds_read_b64_tr_b16 v[116:117], v187 offset:45056
	ds_read_b64_tr_b16 v[118:119], v187 offset:47616
	v_exp_f32_e32 v231, v120
	v_exp_f32_e32 v232, v121
	s_waitcnt lgkmcnt(6)
	v_mfma_f32_32x32x16_bf16 v[48:63], v[224:227], v[154:157], v[48:63]
	ds_read_b64_tr_b16 v[214:215], v187 offset:45120
	ds_read_b64_tr_b16 v[216:217], v187 offset:47680
	v_exp_f32_e32 v224, v122
	v_exp_f32_e32 v225, v123
	s_waitcnt lgkmcnt(6)
	v_mfma_f32_32x32x16_bf16 v[32:47], v[112:115], v[154:157], v[32:47]
	ds_read_b64_tr_b16 v[112:113], v187 offset:45184
	ds_read_b64_tr_b16 v[114:115], v187 offset:47744
	v_exp_f32_e32 v226, v124
	v_exp_f32_e32 v227, v125
	s_waitcnt lgkmcnt(6)
	v_mfma_f32_32x32x16_bf16 v[16:31], v[158:161], v[154:157], v[16:31]
	ds_read_b64_tr_b16 v[120:121], v187 offset:45248
	ds_read_b64_tr_b16 v[122:123], v187 offset:47808
	v_exp_f32_e32 v154, v126
	v_exp_f32_e32 v155, v127
	s_waitcnt lgkmcnt(6)
	v_mfma_f32_32x32x16_bf16 v[64:79], v[116:119], v[150:153], v[64:79]
	ds_read_b64_tr_b16 v[116:117], v187 offset:50176
	ds_read_b64_tr_b16 v[118:119], v187 offset:52736
	v_exp_f32_e32 v156, v96
	v_exp_f32_e32 v157, v97
	s_waitcnt lgkmcnt(6)
	v_mfma_f32_32x32x16_bf16 v[48:63], v[214:217], v[150:153], v[48:63]
	ds_read_b64_tr_b16 v[124:125], v187 offset:50240
	ds_read_b64_tr_b16 v[126:127], v187 offset:52800
	v_exp_f32_e32 v158, v98
	v_exp_f32_e32 v159, v99
	s_waitcnt lgkmcnt(6)
	v_mfma_f32_32x32x16_bf16 v[32:47], v[112:115], v[150:153], v[32:47]
	ds_read_b64_tr_b16 v[96:97], v187 offset:50304
	ds_read_b64_tr_b16 v[98:99], v187 offset:52864
	v_exp_f32_e32 v100, v100
	v_exp_f32_e32 v101, v101
	s_waitcnt lgkmcnt(6)
	v_mfma_f32_32x32x16_bf16 v[16:31], v[120:123], v[150:153], v[16:31]
	ds_read_b64_tr_b16 v[112:113], v187 offset:50368
	ds_read_b64_tr_b16 v[114:115], v187 offset:52928
	s_bitcmp1_b32 s55, 0
	s_cselect_b32 s29, 0x4400, 0
	s_add_i32 s29, s29, 0
	v_add_u32_e32 v187, s29, v182
	s_mulk_i32 s56, 0x5000
	s_waitcnt vmcnt(3)
	ds_write_b128 v187, v[170:173]
	v_add_u32_e32 v187, s29, v190
	s_add_i32 s29, s56, 0
	s_waitcnt vmcnt(2)
	ds_write_b128 v187, v[174:177]
	v_add_u32_e32 v187, s29, v196
	s_waitcnt vmcnt(1)
	ds_write_b128 v187, v[162:165] offset:34816
	v_add_u32_e32 v187, s29, v198
	s_waitcnt vmcnt(0)
	ds_write_b128 v187, v[166:169] offset:34816
	v_exp_f32_e32 v102, v102
	v_exp_f32_e32 v103, v103
	s_waitcnt lgkmcnt(10)
	v_mfma_f32_32x32x16_bf16 v[64:79], v[116:119], v[146:149], v[64:79]
	v_exp_f32_e32 v104, v104
	v_exp_f32_e32 v105, v105
	s_waitcnt lgkmcnt(8)
	v_mfma_f32_32x32x16_bf16 v[48:63], v[124:127], v[146:149], v[48:63]
	v_exp_f32_e32 v106, v106
	v_exp_f32_e32 v107, v107
	s_waitcnt lgkmcnt(6)
	v_mfma_f32_32x32x16_bf16 v[32:47], v[96:99], v[146:149], v[32:47]
	v_exp_f32_e32 v96, v108
	v_exp_f32_e32 v97, v109
	s_waitcnt lgkmcnt(4)
	v_mfma_f32_32x32x16_bf16 v[16:31], v[112:115], v[146:149], v[16:31]
	v_cvt_pk_bf16_f32 v148, v96, v97
	v_cvt_pk_bf16_f32 v147, v106, v107
	v_cvt_pk_bf16_f32 v146, v104, v105
	v_cvt_pk_bf16_f32 v153, v102, v103
	v_cvt_pk_bf16_f32 v152, v100, v101
	v_cvt_pk_bf16_f32 v151, v158, v159
	v_cvt_pk_bf16_f32 v150, v156, v157
	v_cvt_pk_bf16_f32 v157, v154, v155
	v_cvt_pk_bf16_f32 v156, v226, v227
	v_cvt_pk_bf16_f32 v155, v224, v225
	v_cvt_pk_bf16_f32 v154, v231, v232
	v_cvt_pk_bf16_f32 v161, v229, v230
	v_cvt_pk_bf16_f32 v160, v213, v228
	v_cvt_pk_bf16_f32 v159, v189, v212
	v_cvt_pk_bf16_f32 v158, v186, v188
	v_exp_f32_e32 v98, v110
	v_exp_f32_e32 v99, v111
	s_add_i32 s52, s52, 0x230000
	s_addk_i32 s53, 0x4000
	v_cvt_pk_bf16_f32 v149, v98, v99
	s_cmpk_lt_u32 s54, 0x7f
	s_mov_b32 s54, s55
	s_waitcnt lgkmcnt(0)
	s_barrier
	s_cbranch_scc1 .LBB0_479
